# P0: odd workgroups run the filter MLP + weight transposes before the x->bf16 streaming part, even ones after it (latency-bound and bandwidth-bound sub-phases overlap across workgroups)
# baseline (speedup 1.0000x reference)
.LBB0_19:
	s_cmp_lt_i32 s58, 1
	s_cselect_b64 s[10:11], -1, 0
	s_cmp_gt_i32 s58, 0
	s_cselect_b64 s[0:1], -1, 0
	s_cmp_lt_i32 s59, 1
	s_cselect_b64 s[4:5], -1, 0
	s_or_b64 s[0:1], s[0:1], s[4:5]
	s_and_b64 vcc, exec, s[0:1]
	v_bfe_u32 v200, v0, 6, 4
	s_cbranch_vccnz .LBB0_151
	s_cmp_lt_i32 s28, 33
	s_cselect_b64 s[6:7], -1, 0
	s_and_b64 s[0:1], s[6:7], exec
	s_cselect_b32 s3, 0, 16
	s_cmp_ge_i32 s2, s3
	s_cselect_b64 s[0:1], -1, 0
	s_or_b64 s[0:1], s[6:7], s[0:1]
	v_and_b32_e32 v62, 0x3ff, v0
	s_andn2_b64 vcc, exec, s[0:1]
	v_and_b32_e32 v64, 63, v0
	s_cbranch_vccnz .LBB0_130
	s_and_b64 s[0:1], s[0:1], exec
	s_cselect_b32 s34, s3, 0
	s_sub_i32 s0, s2, s3
	v_lshl_add_u32 v66, s0, 3, v200
	s_mov_b32 s30, 0x8000
	s_sub_i32 s29, s28, s34
	v_cmp_gt_i32_e32 vcc, s30, v66
	v_ashrrev_i32_e32 v67, 31, v66
	s_mov_b32 s98, 0
	s_bitcmp1_b32 s2, 0
	s_cbranch_scc0 .Lmy_p0_a_first
	s_mov_b32 s98, 1
	s_mov_b64 s[4:5], exec
	s_branch .LBB0_26
.Lmy_p0_a_first:
	s_and_saveexec_b64 s[4:5], vcc
	s_cbranch_execz .LBB0_26
.Lmy_p0_a:
	v_mbcnt_lo_u32_b32 v1, -1, 0
	v_mbcnt_hi_u32_b32 v3, -1, v1
	v_and_b32_e32 v1, 64, v3
	v_add_u32_e32 v5, 64, v1
	v_xor_b32_e32 v1, 32, v3
	v_cmp_lt_i32_e32 vcc, v1, v5
	v_xor_b32_e32 v7, 16, v3
	v_lshlrev_b64 v[8:9], 12, v[66:67]
	v_cndmask_b32_e32 v1, v3, v1, vcc
	v_cmp_lt_i32_e32 vcc, v7, v5
	v_lshlrev_b32_e32 v2, 3, v64
	s_lshl_b32 s8, s29, 4
	v_cndmask_b32_e32 v7, v3, v7, vcc
	v_lshlrev_b32_e32 v63, 2, v7
	v_xor_b32_e32 v7, 8, v3
	v_cmp_lt_i32_e32 vcc, v7, v5
	v_mov_b32_e32 v69, 0
	v_or_b32_e32 v4, 0x400, v2
	v_cndmask_b32_e32 v7, v3, v7, vcc
	v_lshlrev_b32_e32 v65, 2, v7
	v_xor_b32_e32 v7, 4, v3
	v_cmp_lt_i32_e32 vcc, v7, v5
	v_or_b32_e32 v6, 0x600, v2
	v_lshlrev_b32_e32 v68, 4, v64
	v_cndmask_b32_e32 v7, v3, v7, vcc
	v_lshlrev_b32_e32 v82, 2, v7
	v_xor_b32_e32 v7, 2, v3
	v_cmp_lt_i32_e32 vcc, v7, v5
	s_mov_b64 s[0:1], 0xc00
	s_ashr_i32 s9, s8, 31
	v_cndmask_b32_e32 v7, v3, v7, vcc
	v_lshlrev_b32_e32 v83, 2, v7
	v_xor_b32_e32 v7, 1, v3
	v_cmp_lt_i32_e32 vcc, v7, v5
	s_lshl_b32 s31, s29, 3
	v_lshlrev_b32_e32 v1, 2, v1
	v_cndmask_b32_e32 v3, v3, v7, vcc
	v_lshlrev_b32_e32 v84, 2, v3
	v_and_b32_e32 v3, 63, v62
	v_lshl_or_b32 v8, v3, 4, v8
	v_lshl_add_u64 v[8:9], s[56:57], 0, v[8:9]
	v_lshl_add_u64 v[70:71], s[56:57], 0, v[68:69]
	v_lshl_add_u64 v[72:73], v[8:9], 0, s[0:1]
	s_lshl_b64 s[68:69], s[8:9], 12
	s_mov_b64 s[70:71], 0
	s_movk_i32 s33, 0x4000
	s_waitcnt lgkmcnt(0)
	v_mov_b32_e32 v85, s15
	v_mov_b32_e32 v86, s13
	v_mov_b32_e32 v87, s14
	v_mov_b32_e32 v88, s12
	v_lshlrev_b32_e32 v68, 2, v2
	v_lshlrev_b32_e32 v74, 2, v4
	v_mov_b32_e32 v75, v69
	v_lshlrev_b32_e32 v76, 2, v6
	v_mov_b32_e32 v77, v69
	v_mov_b32_e32 v89, 0x358637bd
	s_mov_b32 s35, 0x800000
	s_movk_i32 s60, 0x7fff
	s_mov_b32 s61, 0xffff0000
	v_mov_b64_e32 v[78:79], v[66:67]
	s_branch .LBB0_24

.LBB0_26:
	s_or_b64 exec, exec, s[4:5]
	s_cmp_eq_u32 s98, 2
	s_cbranch_scc1 .LBB0_130
	s_waitcnt vmcnt(5)
	v_lshlrev_b32_e32 v2, 2, v62
	v_mov_b32_e32 v3, 0
	v_add_u32_e32 v1, 0xfffffe00, v62
	s_waitcnt vmcnt(4)
	v_add_u32_e32 v6, 0, v2
	s_waitcnt lgkmcnt(0)
	v_lshl_add_u64 v[4:5], s[24:25], 0, v[2:3]
	s_mov_b64 s[0:1], 0
	s_mov_b64 s[4:5], 0x800
	s_movk_i32 s8, 0x63f

.LBB0_129:
	s_or_b64 exec, exec, s[4:5]
	s_barrier
	s_cmp_eq_u32 s98, 1
	s_cbranch_scc0 .LBB0_130
	s_mov_b32 s98, 2
	s_sub_i32 s29, s28, s3
	s_sub_i32 s0, s2, s3
	v_lshl_add_u32 v66, s0, 3, v200
	s_mov_b32 s30, 0x8000
	v_cmp_gt_i32_e32 vcc, s30, v66
	v_ashrrev_i32_e32 v67, 31, v66
	s_and_saveexec_b64 s[4:5], vcc
	s_cbranch_execz .LBB0_26
	s_branch .Lmy_p0_a
